# attention loop half-A: p-max subtraction and exp2 block moved ahead of the first tile barrier; rescale temps renamed
# baseline (speedup 1.0000x reference)
; __device__ __forceinline__ void partialSM(f32x16& p0, f32x16& p1, float& m_reg, float& mn, float& alpha) {
;     float pmax = p0[0];
; #pragma unroll
;     for (int r = 1; r < 16; ++r) pmax = fmaxf(pmax, p0[r]);
; #pragma unroll
;     for (int r = 0; r < 16; ++r) pmax = fmaxf(pmax, p1[r]);
;     { auto rr = __builtin_amdgcn_permlane32_swap(__float_as_uint(pmax), __float_as_uint(pmax), false, false);
;       pmax = fmaxf(__uint_as_float(rr[0]), __uint_as_float(rr[1])); }
;     if (__builtin_expect(__all((pmax - m_reg) <= THR), 1)) { mn = m_reg; alpha = 1.f; }
;     else { mn = fmaxf(m_reg, pmax); alpha = __builtin_amdgcn_exp2f(m_reg - mn); m_reg = mn; }
; #pragma unroll
;     for (int r = 0; r < 16; ++r) p0[r] = p0[r] - mn;
; #pragma unroll
;     for (int r = 0; r < 16; ++r) p1[r] = p1[r] - mn;
; #pragma unroll
;     for (int r = 0; r < 16; ++r) p0[r] = __builtin_amdgcn_exp2f(p0[r]);
; }
.LBB0_528:
	v_max_f32_e32 v150, v83, v83
	v_max_f32_e32 v151, v82, v82
	v_max_f32_e32 v150, v151, v150
	v_max3_f32 v150, v150, v84, v85
	v_max3_f32 v150, v150, v86, v87
	v_max3_f32 v150, v150, v88, v89
	v_max3_f32 v150, v150, v90, v91
	v_max3_f32 v150, v150, v92, v93
	v_max3_f32 v150, v150, v94, v95
	v_max3_f32 v150, v150, v96, v97
	v_max3_f32 v150, v150, v66, v67
	v_max3_f32 v150, v150, v68, v69
	v_max3_f32 v150, v150, v70, v71
	v_max3_f32 v150, v150, v72, v73
	v_max3_f32 v150, v150, v74, v75
	v_max3_f32 v150, v150, v76, v77
	v_max3_f32 v150, v150, v78, v79
	v_max3_f32 v150, v150, v80, v81
	v_mov_b32_e32 v151, v150
	s_nop 1
	v_permlane32_swap_b32_e32 v150, v151
	v_max_f32_e32 v151, v151, v151
	v_max_f32_e32 v150, v150, v150
	v_max_f32_e32 v150, v150, v151
	v_sub_f32_e32 v151, v150, v162
	v_cmp_ge_f32_e32 vcc, s37, v151
	v_max_f32_e32 v151, v162, v162
	v_max_f32_e32 v150, v151, v150
	v_sub_f32_e32 v151, v162, v150
	v_exp_f32_e32 v151, v151
	s_cmp_eq_u64 vcc, exec
	s_cselect_b64 s[44:45], -1, 0
	s_nop 0
	v_cndmask_b32_e64 v226, v151, 1.0, s[44:45]
	v_cndmask_b32_e64 v227, v150, v162, s[44:45]
	v_sub_f32_e32 v82, v82, v227
	v_sub_f32_e32 v83, v83, v227
	v_sub_f32_e32 v84, v84, v227
	v_sub_f32_e32 v85, v85, v227
	v_sub_f32_e32 v86, v86, v227
	v_sub_f32_e32 v87, v87, v227
	v_sub_f32_e32 v88, v88, v227
	v_sub_f32_e32 v89, v89, v227
	v_sub_f32_e32 v90, v90, v227
	v_sub_f32_e32 v91, v91, v227
	v_sub_f32_e32 v92, v92, v227
	v_sub_f32_e32 v93, v93, v227
	v_sub_f32_e32 v94, v94, v227
	v_sub_f32_e32 v95, v95, v227
	v_sub_f32_e32 v96, v96, v227
	v_sub_f32_e32 v97, v97, v227
	v_exp_f32_e32 v150, v82
	v_exp_f32_e32 v165, v83
	v_exp_f32_e32 v151, v84
	v_exp_f32_e32 v164, v85
	v_exp_f32_e32 v152, v86
	v_exp_f32_e32 v163, v87
	v_exp_f32_e32 v153, v88
	v_exp_f32_e32 v162, v89
	v_exp_f32_e32 v154, v90
	v_exp_f32_e32 v161, v91
	v_exp_f32_e32 v155, v92
	v_exp_f32_e32 v160, v93
	v_exp_f32_e32 v156, v94
	v_exp_f32_e32 v159, v95
	v_exp_f32_e32 v157, v96
	v_exp_f32_e32 v158, v97
	v_sub_f32_e32 v240, v66, v227
	v_sub_f32_e32 v241, v67, v227
	v_sub_f32_e32 v242, v68, v227
	v_sub_f32_e32 v243, v69, v227
	v_sub_f32_e32 v244, v70, v227
	v_sub_f32_e32 v245, v71, v227
	v_sub_f32_e32 v246, v72, v227
	v_sub_f32_e32 v247, v73, v227
	v_sub_f32_e32 v248, v74, v227
	v_sub_f32_e32 v249, v75, v227
	v_sub_f32_e32 v250, v76, v227
	v_sub_f32_e32 v167, v77, v227
	v_sub_f32_e32 v170, v78, v227
	v_sub_f32_e32 v171, v79, v227
	v_sub_f32_e32 v202, v80, v227
	v_sub_f32_e32 v176, v81, v227
	s_barrier
	s_waitcnt vmcnt(0)
	v_cmp_gt_f32_e32 vcc, 1.0, v226
	s_waitcnt vmcnt(4)
	ds_write_b128 v214, v[130:133]
	s_waitcnt vmcnt(3)
	ds_write_b128 v215, v[134:137]
	s_waitcnt vmcnt(2)
	ds_write_b128 v216, v[138:141] offset:32768
	s_waitcnt vmcnt(1)
	ds_write_b128 v216, v[142:145] offset:45056
	s_waitcnt vmcnt(0)
	ds_write_b128 v217, v[146:149] offset:32768
	s_cbranch_vccz .LBB0_532
	s_and_saveexec_b64 s[4:5], s[42:43]
	ds_write_b32 v197, v226 offset:128
	s_or_b64 exec, exec, s[4:5]
	s_waitcnt lgkmcnt(0)
	ds_read_b128 v[130:133], v196 offset:224
	ds_read_b128 v[134:137], v196 offset:192
	ds_read_b128 v[228:231], v196 offset:160
	ds_read_b128 v[232:235], v196 offset:128
	s_waitcnt lgkmcnt(3)
	v_pk_mul_f32 v[64:65], v[64:65], v[132:133]
	s_waitcnt lgkmcnt(2)
	v_pk_mul_f32 v[60:61], v[60:61], v[136:137]
	s_waitcnt lgkmcnt(1)
	v_pk_mul_f32 v[56:57], v[56:57], v[230:231]
	s_waitcnt lgkmcnt(0)
	v_pk_mul_f32 v[52:53], v[52:53], v[234:235]
	v_pk_mul_f32 v[62:63], v[62:63], v[130:131]
	v_pk_mul_f32 v[58:59], v[58:59], v[134:135]
	v_pk_mul_f32 v[54:55], v[54:55], v[228:229]
	v_pk_mul_f32 v[50:51], v[50:51], v[232:233]
	v_pk_mul_f32 v[48:49], v[48:49], v[132:133]
	v_pk_mul_f32 v[44:45], v[44:45], v[136:137]
	v_pk_mul_f32 v[40:41], v[40:41], v[230:231]
	v_pk_mul_f32 v[36:37], v[36:37], v[234:235]
	v_pk_mul_f32 v[46:47], v[46:47], v[130:131]
	v_pk_mul_f32 v[42:43], v[42:43], v[134:135]
	v_pk_mul_f32 v[38:39], v[38:39], v[228:229]
	v_pk_mul_f32 v[34:35], v[34:35], v[232:233]
	v_pk_mul_f32 v[32:33], v[32:33], v[132:133]
	v_pk_mul_f32 v[28:29], v[28:29], v[136:137]
	v_pk_mul_f32 v[24:25], v[24:25], v[230:231]
	v_pk_mul_f32 v[20:21], v[20:21], v[234:235]
	v_pk_mul_f32 v[30:31], v[30:31], v[130:131]
	v_pk_mul_f32 v[26:27], v[26:27], v[134:135]
	v_pk_mul_f32 v[22:23], v[22:23], v[228:229]
	v_pk_mul_f32 v[18:19], v[18:19], v[232:233]
	v_pk_mul_f32 v[16:17], v[16:17], v[132:133]
	v_pk_mul_f32 v[12:13], v[12:13], v[136:137]
	v_pk_mul_f32 v[8:9], v[8:9], v[230:231]
	v_pk_mul_f32 v[4:5], v[4:5], v[234:235]
	v_pk_mul_f32 v[14:15], v[14:15], v[130:131]
	v_pk_mul_f32 v[10:11], v[10:11], v[134:135]
	v_pk_mul_f32 v[6:7], v[6:7], v[228:229]
	v_pk_mul_f32 v[2:3], v[2:3], v[232:233]
; __device__ __forceinline__ void finishSM(f32x16& p0, f32x16& p1, float alpha, float& l_reg, bf16x8& pa0, bf16x8& pa1, bf16x8& pa2, bf16x8& pa3) {
; #pragma unroll
;     for (int r = 0; r < 16; ++r) p1[r] = __builtin_amdgcn_exp2f(p1[r]);
;     float ps = 0;
; #pragma unroll
;     for (int r = 0; r < 16; ++r) ps += p0[r];
; #pragma unroll
;     for (int r = 0; r < 16; ++r) ps += p1[r];
;     { auto rr = __builtin_amdgcn_permlane32_swap(__float_as_uint(ps), __float_as_uint(ps), false, false);
;       ps = __uint_as_float(rr[0]) + __uint_as_float(rr[1]); }
;     l_reg = l_reg * alpha + ps;
;     ...
;     PK4(p0, 0, pa0); PK4(p0, 8, pa1); PK4(p1, 0, pa2); PK4(p1, 8, pa3);
;     ...
; }
; template <int KB, int DQK>
; __device__ __forceinline__ void qkt(f32x16& p0, f32x16& p1, const char* K_lds, int r32, int hi, const bf16x8* qr, const char* qrl) {
;     constexpr int SHMK = 64 * DQK * 2, NF = DQK / 16, NFR = NF > 8 ? 8 : NF;
;     p0 = f32x16{}; p1 = f32x16{};
;     const char* kb[4];
; #pragma unroll
;     for (int dd = 0; dd < 4; ++dd) kb[dd] = K_lds + KB * SHMK + kswz<DQK>(r32, (dd * 16 + hi * 8) * 2);
; #pragma unroll
;     for (int d0 = 0; d0 < NF; ++d0) { const char* a = kb[d0 & 3] + (d0 >> 2) * 128;
;         bf16x8 b0 = *reinterpret_cast<const bf16x8*>(a);
;         bf16x8 b1 = *reinterpret_cast<const bf16x8*>(a + 32 * DQK * 2);
;         bf16x8 q; if (d0 < NFR) q = qr[d0]; else q = *reinterpret_cast<const bf16x8*>(qrl + (d0 - NFR) * 1024);
;         p0 = __builtin_amdgcn_mfma_f32_32x32x16_bf16(b0, q, p0, 0, 0, 0);
;         p1 = __builtin_amdgcn_mfma_f32_32x32x16_bf16(b1, q, p1, 0, 0, 0); }
; }
.LBB0_532:
	s_waitcnt lgkmcnt(0)
	s_barrier
	ds_read_b128 v[66:69], v212 offset:32768
	ds_read_b128 v[70:73], v212 offset:45056
	ds_read_b128 v[228:231], v213 offset:32768
	ds_read_b128 v[232:235], v213 offset:45056
	v_exp_f32_e32 v177, v240
	v_exp_f32_e32 v167, v167
	s_waitcnt lgkmcnt(3)
	v_mfma_f32_32x32x16_bf16 v[82:97], v[66:69], v[126:129], 0
	v_exp_f32_e32 v170, v170
	v_exp_f32_e32 v171, v171
	v_exp_f32_e32 v202, v202
	v_exp_f32_e32 v176, v176
	s_waitcnt lgkmcnt(2)
	v_mfma_f32_32x32x16_bf16 v[66:81], v[70:73], v[126:129], 0
	s_waitcnt lgkmcnt(1)
	v_mfma_f32_32x32x16_bf16 v[82:97], v[228:231], v[122:125], v[82:97]
	s_waitcnt lgkmcnt(0)
	v_mfma_f32_32x32x16_bf16 v[66:81], v[232:235], v[122:125], v[66:81]
	ds_read_b128 v[228:231], v211 offset:32768
	ds_read_b128 v[232:235], v211 offset:45056
	s_waitcnt lgkmcnt(1)
	v_mfma_f32_32x32x16_bf16 v[82:97], v[228:231], v[118:121], v[82:97]
	s_waitcnt lgkmcnt(0)
	v_mfma_f32_32x32x16_bf16 v[66:81], v[232:235], v[118:121], v[66:81]
	ds_read_b128 v[228:231], v210 offset:32768
	ds_read_b128 v[232:235], v210 offset:45056
	s_waitcnt lgkmcnt(1)
	v_mfma_f32_32x32x16_bf16 v[82:97], v[228:231], v[114:117], v[82:97]
	s_waitcnt lgkmcnt(0)
	v_mfma_f32_32x32x16_bf16 v[66:81], v[232:235], v[114:117], v[66:81]
	ds_read_b128 v[228:231], v212 offset:32896
	ds_read_b128 v[232:235], v212 offset:45184
	s_waitcnt lgkmcnt(1)
	v_mfma_f32_32x32x16_bf16 v[82:97], v[228:231], v[102:105], v[82:97]
	s_waitcnt lgkmcnt(0)
	v_mfma_f32_32x32x16_bf16 v[66:81], v[232:235], v[102:105], v[66:81]
	ds_read_b128 v[228:231], v213 offset:32896
	ds_read_b128 v[232:235], v213 offset:45184
	s_waitcnt lgkmcnt(1)
	v_mfma_f32_32x32x16_bf16 v[82:97], v[228:231], v[98:101], v[82:97]
	s_waitcnt lgkmcnt(0)
	v_mfma_f32_32x32x16_bf16 v[66:81], v[232:235], v[98:101], v[66:81]
	ds_read_b128 v[228:231], v211 offset:32896
	ds_read_b128 v[232:235], v211 offset:45184
	s_waitcnt lgkmcnt(1)
	v_mfma_f32_32x32x16_bf16 v[82:97], v[228:231], v[110:113], v[82:97]
	s_waitcnt lgkmcnt(0)
	v_mfma_f32_32x32x16_bf16 v[66:81], v[232:235], v[110:113], v[66:81]
	ds_read_b128 v[228:231], v210 offset:32896
	ds_read_b128 v[232:235], v210 offset:45184
	s_waitcnt lgkmcnt(1)
	v_mfma_f32_32x32x16_bf16 v[82:97], v[228:231], v[106:109], v[82:97]
	s_waitcnt lgkmcnt(0)
	v_mfma_f32_32x32x16_bf16 v[66:81], v[232:235], v[106:109], v[66:81]
	ds_read_b128 v[228:231], v212 offset:33024
	ds_read_b128 v[232:235], v212 offset:45312
	ds_read_b128 v[236:239], v209
	s_waitcnt lgkmcnt(0)
	v_mfma_f32_32x32x16_bf16 v[82:97], v[228:231], v[236:239], v[82:97]
	v_mfma_f32_32x32x16_bf16 v[66:81], v[232:235], v[236:239], v[66:81]
	ds_read_b128 v[228:231], v213 offset:33024
	ds_read_b128 v[232:235], v213 offset:45312
	ds_read_b128 v[236:239], v209 offset:1024
	s_waitcnt lgkmcnt(0)
	v_mfma_f32_32x32x16_bf16 v[82:97], v[228:231], v[236:239], v[82:97]
	v_mfma_f32_32x32x16_bf16 v[66:81], v[232:235], v[236:239], v[66:81]
	ds_read_b128 v[228:231], v211 offset:33024
	ds_read_b128 v[232:235], v211 offset:45312
	ds_read_b128 v[236:239], v209 offset:2048
	s_waitcnt lgkmcnt(0)
	v_mfma_f32_32x32x16_bf16 v[82:97], v[228:231], v[236:239], v[82:97]
	v_mfma_f32_32x32x16_bf16 v[66:81], v[232:235], v[236:239], v[66:81]
	ds_read_b128 v[228:231], v210 offset:33024
	ds_read_b128 v[232:235], v210 offset:45312
	ds_read_b128 v[236:239], v209 offset:3072
	s_waitcnt lgkmcnt(0)
	v_mfma_f32_32x32x16_bf16 v[82:97], v[228:231], v[236:239], v[82:97]
	v_add_f32_e32 v228, 0, v150
	v_add_f32_e32 v228, v165, v228
	v_add_f32_e32 v228, v151, v228
	v_add_f32_e32 v228, v164, v228
	v_add_f32_e32 v228, v152, v228
	v_add_f32_e32 v228, v163, v228
	v_add_f32_e32 v228, v153, v228
	v_add_f32_e32 v228, v162, v228
	v_add_f32_e32 v228, v154, v228
	v_add_f32_e32 v228, v161, v228
	v_add_f32_e32 v228, v155, v228
	v_add_f32_e32 v228, v160, v228
	v_add_f32_e32 v228, v156, v228
	v_exp_f32_e32 v230, v241
	v_add_f32_e32 v228, v159, v228
	v_exp_f32_e32 v231, v242
	v_add_f32_e32 v228, v157, v228
	v_mfma_f32_32x32x16_bf16 v[66:81], v[232:235], v[236:239], v[66:81]
	v_exp_f32_e32 v232, v243
	v_add_f32_e32 v228, v158, v228
	v_exp_f32_e32 v233, v244
	v_add_f32_e32 v228, v177, v228
	v_exp_f32_e32 v234, v245
	v_add_f32_e32 v228, v230, v228
	v_exp_f32_e32 v235, v246
	v_add_f32_e32 v228, v231, v228
	v_exp_f32_e32 v236, v247
	v_add_f32_e32 v228, v232, v228
	v_exp_f32_e32 v237, v248
	v_add_f32_e32 v228, v233, v228
	v_exp_f32_e32 v238, v249
	v_add_f32_e32 v228, v234, v228
	v_exp_f32_e32 v239, v250
	v_add_f32_e32 v228, v235, v228
	v_add_f32_e32 v228, v236, v228
	v_add_f32_e32 v228, v237, v228
	v_add_f32_e32 v228, v238, v228
	v_add_f32_e32 v228, v239, v228
	v_add_f32_e32 v228, v167, v228
	v_add_f32_e32 v228, v170, v228
	v_add_f32_e32 v228, v171, v228
	v_add_f32_e32 v228, v202, v228
	v_add_f32_e32 v228, v176, v228
	v_mov_b32_e32 v229, v228
	v_cvt_pk_bf16_f32 v150, v150, v165
	v_cvt_pk_bf16_f32 v151, v151, v164
	v_cvt_pk_bf16_f32 v152, v152, v163
	v_cvt_pk_bf16_f32 v153, v153, v162
	v_cvt_pk_bf16_f32 v154, v154, v161
	v_cvt_pk_bf16_f32 v155, v155, v160
	v_cvt_pk_bf16_f32 v156, v156, v159
	v_cvt_pk_bf16_f32 v157, v157, v158
	v_cvt_pk_bf16_f32 v158, v177, v230
	v_cvt_pk_bf16_f32 v159, v231, v232
	v_cvt_pk_bf16_f32 v160, v233, v234
	v_cvt_pk_bf16_f32 v161, v235, v236
	v_cvt_pk_bf16_f32 v162, v237, v238
	v_cvt_pk_bf16_f32 v163, v239, v167
	v_cvt_pk_bf16_f32 v164, v170, v171
	v_cvt_pk_bf16_f32 v165, v202, v176
	s_nop 1
	v_permlane32_swap_b32_e32 v228, v229
	v_permlane32_swap_b32_e32 v150, v152
	v_permlane32_swap_b32_e32 v151, v153
	v_permlane32_swap_b32_e32 v154, v156
	v_permlane32_swap_b32_e32 v155, v157
	v_permlane32_swap_b32_e32 v158, v160
	v_permlane32_swap_b32_e32 v159, v161
	v_permlane32_swap_b32_e32 v162, v164
	v_permlane32_swap_b32_e32 v163, v165
	s_add_i32 s4, s3, 1
	s_cmp_lt_u32 s4, s30
	s_cselect_b64 s[16:17], -1, 0
	s_cmp_ge_u32 s4, s30
	s_cbranch_scc1 .LBB0_534
	v_add_co_u32_e32 v130, vcc, 0x1ec60000, v190
	s_nop 1
	v_addc_co_u32_e32 v131, vcc, 0, v191, vcc
	v_add_co_u32_e32 v134, vcc, 0x1ec70000, v190
	s_nop 1
	v_addc_co_u32_e32 v135, vcc, 0, v191, vcc
	v_add_co_u32_e32 v138, vcc, 0x1ec60000, v186
	global_load_dwordx4 v[130:133], v[130:131], off offset:1024
	s_nop 0
	global_load_dwordx4 v[134:137], v[134:135], off offset:1024
	v_addc_co_u32_e32 v139, vcc, 0, v187, vcc
	v_add_co_u32_e32 v142, vcc, 0x1ec70000, v186
	s_nop 1
	v_addc_co_u32_e32 v143, vcc, 0, v187, vcc
	v_add_co_u32_e32 v146, vcc, 0x18cd8000, v188
	global_load_dwordx4 v[138:141], v[138:139], off
	s_nop 0
	global_load_dwordx4 v[142:145], v[142:143], off
	v_addc_co_u32_e32 v147, vcc, 0, v189, vcc
	global_load_dwordx4 v[146:149], v[146:147], off offset:1280

; __device__ __forceinline__ void partialSM(f32x16& p0, f32x16& p1, float& m_reg, float& mn, float& alpha) {
;     float pmax = p0[0];
; #pragma unroll
;     for (int r = 1; r < 16; ++r) pmax = fmaxf(pmax, p0[r]);
; #pragma unroll
;     for (int r = 0; r < 16; ++r) pmax = fmaxf(pmax, p1[r]);
;     { auto rr = __builtin_amdgcn_permlane32_swap(__float_as_uint(pmax), __float_as_uint(pmax), false, false);
;       pmax = fmaxf(__uint_as_float(rr[0]), __uint_as_float(rr[1])); }
;     if (__builtin_expect(__all((pmax - m_reg) <= THR), 1)) { mn = m_reg; alpha = 1.f; }
;     else { mn = fmaxf(m_reg, pmax); alpha = __builtin_amdgcn_exp2f(m_reg - mn); m_reg = mn; }
; #pragma unroll
;     for (int r = 0; r < 16; ++r) p0[r] = p0[r] - mn;
; #pragma unroll
;     for (int r = 0; r < 16; ++r) p1[r] = p1[r] - mn;
; #pragma unroll
;     for (int r = 0; r < 16; ++r) p0[r] = __builtin_amdgcn_exp2f(p0[r]);
; }
.LBB0_697:
	v_max_f32_e32 v126, v83, v83
	v_max_f32_e32 v127, v82, v82
	v_max_f32_e32 v126, v127, v126
	v_max3_f32 v126, v126, v84, v85
	v_max3_f32 v126, v126, v86, v87
	v_max3_f32 v126, v126, v88, v89
	v_max3_f32 v126, v126, v90, v91
	v_max3_f32 v126, v126, v92, v93
	v_max3_f32 v126, v126, v94, v95
	v_max3_f32 v126, v126, v96, v97
	v_max3_f32 v126, v126, v66, v67
	v_max3_f32 v126, v126, v68, v69
	v_max3_f32 v126, v126, v70, v71
	v_max3_f32 v126, v126, v72, v73
	v_max3_f32 v126, v126, v74, v75
	v_max3_f32 v126, v126, v76, v77
	v_max3_f32 v126, v126, v78, v79
	v_max3_f32 v126, v126, v80, v81
	v_mov_b32_e32 v127, v126
	s_nop 1
	v_permlane32_swap_b32_e32 v126, v127
	v_max_f32_e32 v127, v127, v127
	v_max_f32_e32 v126, v126, v126
	v_max_f32_e32 v126, v126, v127
	v_sub_f32_e32 v127, v126, v130
	v_cmp_ge_f32_e32 vcc, s37, v127
	v_max_f32_e32 v127, v130, v130
	v_max_f32_e32 v126, v127, v126
	v_sub_f32_e32 v127, v130, v126
	v_exp_f32_e32 v127, v127
	s_cmp_eq_u64 vcc, exec
	s_cselect_b64 s[44:45], -1, 0
	s_nop 0
	v_cndmask_b32_e64 v182, v127, 1.0, s[44:45]
	v_cndmask_b32_e64 v183, v126, v130, s[44:45]
	v_sub_f32_e32 v82, v82, v183
	v_sub_f32_e32 v83, v83, v183
	v_sub_f32_e32 v84, v84, v183
	v_sub_f32_e32 v85, v85, v183
	v_sub_f32_e32 v86, v86, v183
	v_sub_f32_e32 v87, v87, v183
	v_sub_f32_e32 v88, v88, v183
	v_sub_f32_e32 v89, v89, v183
	v_sub_f32_e32 v90, v90, v183
	v_sub_f32_e32 v91, v91, v183
	v_sub_f32_e32 v92, v92, v183
	v_sub_f32_e32 v93, v93, v183
	v_sub_f32_e32 v94, v94, v183
	v_sub_f32_e32 v95, v95, v183
	v_sub_f32_e32 v96, v96, v183
	v_sub_f32_e32 v97, v97, v183
	v_exp_f32_e32 v126, v82
	v_exp_f32_e32 v141, v83
	v_exp_f32_e32 v127, v84
	v_exp_f32_e32 v140, v85
	v_exp_f32_e32 v128, v86
	v_exp_f32_e32 v139, v87
	v_exp_f32_e32 v129, v88
	v_exp_f32_e32 v138, v89
	v_exp_f32_e32 v130, v90
	v_exp_f32_e32 v137, v91
	v_exp_f32_e32 v131, v92
	v_exp_f32_e32 v136, v93
	v_exp_f32_e32 v132, v94
	v_exp_f32_e32 v135, v95
	v_exp_f32_e32 v133, v96
	v_exp_f32_e32 v134, v97
	v_sub_f32_e32 v167, v66, v183
	v_sub_f32_e32 v170, v67, v183
	v_sub_f32_e32 v171, v68, v183
	v_sub_f32_e32 v176, v69, v183
	v_sub_f32_e32 v177, v70, v183
	v_sub_f32_e32 v192, v71, v183
	v_sub_f32_e32 v193, v72, v183
	v_sub_f32_e32 v194, v73, v183
	v_sub_f32_e32 v195, v74, v183
	v_sub_f32_e32 v196, v75, v183
	v_sub_f32_e32 v197, v76, v183
	v_sub_f32_e32 v202, v77, v183
	v_sub_f32_e32 v207, v78, v183
	v_sub_f32_e32 v208, v79, v183
	v_sub_f32_e32 v209, v80, v183
	v_sub_f32_e32 v210, v81, v183
	s_barrier
	s_waitcnt vmcnt(0)
	v_cmp_gt_f32_e32 vcc, 1.0, v182
	s_waitcnt vmcnt(2)
	ds_write_b128 v158, v[114:117]
	s_waitcnt vmcnt(1)
	ds_write_b128 v159, v[118:121]
	s_waitcnt vmcnt(0)
	ds_write_b128 v160, v[122:125] offset:32768
	s_cbranch_vccz .LBB0_701
	s_and_saveexec_b64 s[4:5], s[42:43]
	ds_write_b32 v155, v182 offset:128
	s_or_b64 exec, exec, s[4:5]
	s_waitcnt lgkmcnt(0)
	ds_read_b128 v[114:117], v154 offset:224
	ds_read_b128 v[118:121], v154 offset:192
	ds_read_b128 v[184:187], v154 offset:160
	ds_read_b128 v[188:191], v154 offset:128
	s_waitcnt lgkmcnt(3)
	v_pk_mul_f32 v[64:65], v[64:65], v[116:117]
	s_waitcnt lgkmcnt(2)
	v_pk_mul_f32 v[60:61], v[60:61], v[120:121]
	s_waitcnt lgkmcnt(1)
	v_pk_mul_f32 v[56:57], v[56:57], v[186:187]
	s_waitcnt lgkmcnt(0)
	v_pk_mul_f32 v[52:53], v[52:53], v[190:191]
	v_pk_mul_f32 v[62:63], v[62:63], v[114:115]
	v_pk_mul_f32 v[58:59], v[58:59], v[118:119]
	v_pk_mul_f32 v[54:55], v[54:55], v[184:185]
	v_pk_mul_f32 v[50:51], v[50:51], v[188:189]
	v_pk_mul_f32 v[48:49], v[48:49], v[116:117]
	v_pk_mul_f32 v[44:45], v[44:45], v[120:121]
	v_pk_mul_f32 v[40:41], v[40:41], v[186:187]
	v_pk_mul_f32 v[36:37], v[36:37], v[190:191]
	v_pk_mul_f32 v[46:47], v[46:47], v[114:115]
	v_pk_mul_f32 v[42:43], v[42:43], v[118:119]
	v_pk_mul_f32 v[38:39], v[38:39], v[184:185]
	v_pk_mul_f32 v[34:35], v[34:35], v[188:189]
	v_pk_mul_f32 v[32:33], v[32:33], v[116:117]
	v_pk_mul_f32 v[28:29], v[28:29], v[120:121]
	v_pk_mul_f32 v[24:25], v[24:25], v[186:187]
	v_pk_mul_f32 v[20:21], v[20:21], v[190:191]
	v_pk_mul_f32 v[30:31], v[30:31], v[114:115]
	v_pk_mul_f32 v[26:27], v[26:27], v[118:119]
	v_pk_mul_f32 v[22:23], v[22:23], v[184:185]
	v_pk_mul_f32 v[18:19], v[18:19], v[188:189]
	v_pk_mul_f32 v[16:17], v[16:17], v[116:117]
	v_pk_mul_f32 v[12:13], v[12:13], v[120:121]
	v_pk_mul_f32 v[8:9], v[8:9], v[186:187]
	v_pk_mul_f32 v[4:5], v[4:5], v[190:191]
	v_pk_mul_f32 v[14:15], v[14:15], v[114:115]
	v_pk_mul_f32 v[10:11], v[10:11], v[118:119]
	v_pk_mul_f32 v[6:7], v[6:7], v[184:185]
	v_pk_mul_f32 v[2:3], v[2:3], v[188:189]
; __device__ __forceinline__ void finishSM(f32x16& p0, f32x16& p1, float alpha, float& l_reg, bf16x8& pa0, bf16x8& pa1, bf16x8& pa2, bf16x8& pa3) {
; #pragma unroll
;     for (int r = 0; r < 16; ++r) p1[r] = __builtin_amdgcn_exp2f(p1[r]);
;     float ps = 0;
; #pragma unroll
;     for (int r = 0; r < 16; ++r) ps += p0[r];
; #pragma unroll
;     for (int r = 0; r < 16; ++r) ps += p1[r];
;     { auto rr = __builtin_amdgcn_permlane32_swap(__float_as_uint(ps), __float_as_uint(ps), false, false);
;       ps = __uint_as_float(rr[0]) + __uint_as_float(rr[1]); }
;     l_reg = l_reg * alpha + ps;
;     ...
;     PK4(p0, 0, pa0); PK4(p0, 8, pa1); PK4(p1, 0, pa2); PK4(p1, 8, pa3);
;     ...
; }
; template <int KB, int DQK>
; __device__ __forceinline__ void qkt(f32x16& p0, f32x16& p1, const char* K_lds, int r32, int hi, const bf16x8* qr, const char* qrl) {
;     constexpr int SHMK = 64 * DQK * 2, NF = DQK / 16, NFR = NF > 8 ? 8 : NF;
;     p0 = f32x16{}; p1 = f32x16{};
;     const char* kb[4];
; #pragma unroll
;     for (int dd = 0; dd < 4; ++dd) kb[dd] = K_lds + KB * SHMK + kswz<DQK>(r32, (dd * 16 + hi * 8) * 2);
; #pragma unroll
;     for (int d0 = 0; d0 < NF; ++d0) { const char* a = kb[d0 & 3] + (d0 >> 2) * 128;
;         bf16x8 b0 = *reinterpret_cast<const bf16x8*>(a);
;         bf16x8 b1 = *reinterpret_cast<const bf16x8*>(a + 32 * DQK * 2);
;         bf16x8 q; if (d0 < NFR) q = qr[d0]; else q = *reinterpret_cast<const bf16x8*>(qrl + (d0 - NFR) * 1024);
;         p0 = __builtin_amdgcn_mfma_f32_32x32x16_bf16(b0, q, p0, 0, 0, 0);
;         p1 = __builtin_amdgcn_mfma_f32_32x32x16_bf16(b1, q, p1, 0, 0, 0); }
; }
.LBB0_701:
	s_waitcnt lgkmcnt(0)
	s_barrier
	ds_read_b128 v[66:69], v161 offset:32768
	ds_read_b128 v[70:73], v161 offset:36864
	ds_read_b128 v[184:187], v162 offset:32768
	ds_read_b128 v[188:191], v162 offset:36864
	v_exp_f32_e32 v167, v167
	v_exp_f32_e32 v170, v170
	s_waitcnt lgkmcnt(3)
	v_mfma_f32_32x32x16_bf16 v[82:97], v[66:69], v[110:113], 0
	v_exp_f32_e32 v171, v171
	v_exp_f32_e32 v176, v176
	v_exp_f32_e32 v177, v177
	s_waitcnt lgkmcnt(2)
	v_mfma_f32_32x32x16_bf16 v[66:81], v[70:73], v[110:113], 0
	s_waitcnt lgkmcnt(1)
	v_mfma_f32_32x32x16_bf16 v[82:97], v[184:187], v[106:109], v[82:97]
	s_waitcnt lgkmcnt(0)
	v_mfma_f32_32x32x16_bf16 v[66:81], v[188:191], v[106:109], v[66:81]
	ds_read_b128 v[184:187], v163 offset:32768
	ds_read_b128 v[188:191], v163 offset:36864
	s_waitcnt lgkmcnt(1)
	v_mfma_f32_32x32x16_bf16 v[82:97], v[184:187], v[102:105], v[82:97]
	s_waitcnt lgkmcnt(0)
	v_mfma_f32_32x32x16_bf16 v[66:81], v[188:191], v[102:105], v[66:81]
	ds_read_b128 v[184:187], v164 offset:32768
	ds_read_b128 v[188:191], v164 offset:36864
	s_waitcnt lgkmcnt(1)
	v_mfma_f32_32x32x16_bf16 v[82:97], v[184:187], v[98:101], v[82:97]
	v_add_f32_e32 v184, 0, v126
	v_add_f32_e32 v184, v141, v184
	v_add_f32_e32 v184, v127, v184
	v_add_f32_e32 v184, v140, v184
	v_add_f32_e32 v184, v128, v184
	v_add_f32_e32 v184, v139, v184
	v_add_f32_e32 v184, v129, v184
	v_add_f32_e32 v184, v138, v184
	v_add_f32_e32 v184, v130, v184
	v_add_f32_e32 v184, v137, v184
	v_add_f32_e32 v184, v131, v184
	v_add_f32_e32 v184, v136, v184
	v_add_f32_e32 v184, v132, v184
	v_add_f32_e32 v184, v135, v184
	v_add_f32_e32 v184, v133, v184
	v_add_f32_e32 v184, v134, v184
	v_add_f32_e32 v184, v167, v184
	v_exp_f32_e32 v186, v192
	v_add_f32_e32 v184, v170, v184
	v_exp_f32_e32 v187, v193
	v_add_f32_e32 v184, v171, v184
	s_waitcnt lgkmcnt(0)
	v_mfma_f32_32x32x16_bf16 v[66:81], v[188:191], v[98:101], v[66:81]
	v_exp_f32_e32 v188, v194
	v_add_f32_e32 v184, v176, v184
	v_exp_f32_e32 v189, v195
	v_add_f32_e32 v184, v177, v184
	v_exp_f32_e32 v190, v196
	v_add_f32_e32 v184, v186, v184
	v_exp_f32_e32 v191, v197
	v_add_f32_e32 v184, v187, v184
	v_exp_f32_e32 v192, v202
	v_add_f32_e32 v184, v188, v184
	v_exp_f32_e32 v193, v207
	v_add_f32_e32 v184, v189, v184
	v_exp_f32_e32 v194, v208
	v_add_f32_e32 v184, v190, v184
	v_exp_f32_e32 v195, v209
	v_add_f32_e32 v184, v191, v184
	v_exp_f32_e32 v196, v210
	v_add_f32_e32 v184, v192, v184
	v_add_f32_e32 v184, v193, v184
	v_add_f32_e32 v184, v194, v184
	v_add_f32_e32 v184, v195, v184
	v_add_f32_e32 v184, v196, v184
	v_mov_b32_e32 v185, v184
	v_cvt_pk_bf16_f32 v126, v126, v141
	v_cvt_pk_bf16_f32 v127, v127, v140
	v_cvt_pk_bf16_f32 v128, v128, v139
	v_cvt_pk_bf16_f32 v129, v129, v138
	v_cvt_pk_bf16_f32 v130, v130, v137
	v_cvt_pk_bf16_f32 v131, v131, v136
	v_cvt_pk_bf16_f32 v132, v132, v135
	v_cvt_pk_bf16_f32 v133, v133, v134
	v_cvt_pk_bf16_f32 v138, v167, v170
	v_cvt_pk_bf16_f32 v139, v171, v176
	v_cvt_pk_bf16_f32 v140, v177, v186
	v_cvt_pk_bf16_f32 v141, v187, v188
	v_cvt_pk_bf16_f32 v134, v189, v190
	v_cvt_pk_bf16_f32 v135, v191, v192
	v_cvt_pk_bf16_f32 v136, v193, v194
	v_cvt_pk_bf16_f32 v137, v195, v196
	s_nop 1
	v_permlane32_swap_b32_e32 v184, v185
	v_permlane32_swap_b32_e32 v126, v128
	v_permlane32_swap_b32_e32 v127, v129
	v_permlane32_swap_b32_e32 v130, v132
	v_permlane32_swap_b32_e32 v131, v133
	v_permlane32_swap_b32_e32 v138, v140
	v_permlane32_swap_b32_e32 v139, v141
	v_permlane32_swap_b32_e32 v134, v136
	v_permlane32_swap_b32_e32 v135, v137
	s_add_i32 s4, s34, 1
	s_cmp_lt_u32 s4, s35
	s_cselect_b64 s[16:17], -1, 0
	s_cmp_ge_u32 s4, s35
	s_cbranch_scc1 .LBB0_703
	v_add_co_u32_e32 v114, vcc, 0x18cd8000, v146
	s_nop 1
	v_addc_co_u32_e32 v115, vcc, 0, v147, vcc
	v_add_co_u32_e32 v118, vcc, 0x18cfc000, v146
	s_nop 1
	v_addc_co_u32_e32 v119, vcc, 0, v147, vcc
	v_add_co_u32_e32 v122, vcc, 0x18cd8000, v148
	global_load_dwordx4 v[114:117], v[114:115], off offset:3456
	s_nop 0
	global_load_dwordx4 v[118:121], v[118:119], off offset:3456
	v_addc_co_u32_e32 v123, vcc, 0, v149, vcc
	global_load_dwordx4 v[122:125], v[122:123], off offset:2432
